# NA attention phase: one static s_setprio 1 for waves 4-7 for the whole phase (reset to 0 at phase end)
# speedup vs baseline: 1.0006x; 1.0006x over previous
.LBB0_2269:
	s_cmp_gt_i32 s66, 28
	s_cselect_b64 s[6:7], -1, 0
	s_cmp_lt_i32 s67, 29
	s_cselect_b64 s[8:9], -1, 0
	s_or_b64 s[6:7], s[6:7], s[8:9]
	s_and_b64 vcc, exec, s[6:7]
	s_cbranch_vccnz .LBB0_2392
	v_readfirstlane_b32 s98, v202
	s_nop 3
	s_cmp_ge_u32 s98, 0x100
	s_cbranch_scc0 .Lna_prio_skip
	s_setprio 1
.Lna_prio_skip:
	s_mov_b64 s[6:7], s[0:1]
	v_mov_b32_e32 v72, v202
	s_cmpk_gt_i32 s2, 0x3ff
	s_cbranch_scc1 .LBB0_2338
	v_lshrrev_b32_e32 v0, 2, v72
	s_load_dwordx2 s[8:9], s[6:7], 0xf8
	s_load_dwordx2 s[52:53], s[6:7], 0xc8
	v_and_b32_e32 v0, 48, v0
	v_sub_u32_e64 v2, v0, 8 clamp
	v_and_b32_e32 v8, 15, v72
	v_min_u32_e32 v6, 32, v2
	v_bfe_u32 v2, v72, 5, 1
	v_or_b32_e32 v0, v0, v8
	v_mov_b32_e32 v77, 0
	v_sub_u32_e64 v3, v0, 8 clamp
	v_lshlrev_b32_e32 v74, 4, v2
	v_mov_b32_e32 v75, v77
	v_min_u32_e32 v9, 48, v3
	v_or_b32_e32 v126, 0x100, v0
	v_lshlrev_b32_e32 v0, 2, v2
	v_lshlrev_b32_e32 v127, 3, v2
	s_waitcnt lgkmcnt(0)
	v_lshl_add_u64 v[2:3], s[8:9], 0, v[74:75]
	s_mov_b64 s[6:7], 0x11030000
	v_lshl_add_u64 v[78:79], v[2:3], 0, s[6:7]
	v_ashrrev_i32_e32 v80, 3, v72
	v_and_b32_e32 v3, 7, v72
	s_movk_i32 s3, 0x90
	v_and_b32_e32 v1, 31, v72
	v_lshlrev_b32_e32 v2, 3, v3
	v_lshlrev_b32_e32 v76, 4, v3
	v_mul_lo_u32 v3, v80, s3
	v_add3_u32 v75, 0, v3, v76
	v_add_u32_e32 v3, v6, v1
	v_mul_u32_u24_e32 v129, 0x90, v1
	v_mbcnt_lo_u32_b32 v1, -1, 0
	v_lshl_add_u64 v[4:5], s[8:9], 0, v[76:77]
	s_mov_b64 s[6:7], 0x140f0000
	v_mbcnt_hi_u32_b32 v1, -1, v1
	v_lshl_add_u64 v[82:83], v[4:5], 0, s[6:7]
	v_and_b32_e32 v5, 64, v1
	s_add_u32 s54, s8, 0x171b0000
	v_xor_b32_e32 v4, 32, v1
	v_add_u32_e32 v5, 64, v5
	s_addc_u32 s55, s9, 0
	v_cmp_lt_i32_e32 vcc, v4, v5
	s_add_u32 s56, s8, 0xc300000
	v_add_u32_e32 v10, 16, v9
	v_mul_u32_u24_e32 v128, 0x90, v3
	v_or_b32_e32 v3, v6, v0
	v_cndmask_b32_e32 v1, v1, v4, vcc
	s_addc_u32 s57, s9, 0
	v_lshlrev_b32_e32 v130, 2, v1
	v_cmp_ge_u32_e32 vcc, v3, v9
	v_cmp_lt_u32_e64 s[8:9], v3, v10
	v_or_b32_e32 v1, 1, v3
	s_and_b64 s[8:9], vcc, s[8:9]
	v_cmp_lt_u32_e32 vcc, v1, v9
	v_cmp_ge_u32_e64 s[10:11], v1, v10
	v_or_b32_e32 v4, 2, v3
	s_or_b64 s[10:11], vcc, s[10:11]
	v_cmp_lt_u32_e32 vcc, v4, v9
	v_cmp_ge_u32_e64 s[12:13], v4, v10
	v_or_b32_e32 v5, 3, v3
	s_or_b64 s[12:13], vcc, s[12:13]
	v_cmp_lt_u32_e32 vcc, v5, v9
	v_cmp_ge_u32_e64 s[14:15], v5, v10
	v_add_u32_e32 v11, 8, v3
	s_or_b64 s[14:15], vcc, s[14:15]
	v_cmp_lt_u32_e32 vcc, v11, v9
	v_cmp_ge_u32_e64 s[16:17], v11, v10
	v_add_u32_e32 v12, 9, v3
	s_or_b64 s[16:17], vcc, s[16:17]
	v_cmp_lt_u32_e32 vcc, v12, v9
	v_cmp_ge_u32_e64 s[18:19], v12, v10
	v_add_u32_e32 v13, 10, v3
	s_or_b64 s[18:19], vcc, s[18:19]
	v_cmp_lt_u32_e32 vcc, v13, v9
	v_cmp_ge_u32_e64 s[20:21], v13, v10
	v_add_u32_e32 v14, 11, v3
	s_or_b64 s[20:21], vcc, s[20:21]
	v_cmp_lt_u32_e32 vcc, v14, v9
	v_cmp_ge_u32_e64 s[22:23], v14, v10
	v_add_u32_e32 v15, 16, v3
	s_or_b64 s[22:23], vcc, s[22:23]
	v_cmp_ge_u32_e32 vcc, v15, v9
	v_cmp_lt_u32_e64 s[24:25], v3, v9
	v_add_u32_e32 v16, 17, v3
	s_and_b64 s[24:25], s[24:25], vcc
	v_cmp_ge_u32_e32 vcc, v16, v9
	v_cmp_lt_u32_e64 s[26:27], v16, v10
	v_add_u32_e32 v17, 18, v3
	s_and_b64 s[26:27], vcc, s[26:27]
	v_cmp_lt_u32_e32 vcc, v17, v9
	v_cmp_ge_u32_e64 s[28:29], v17, v10
	v_add_u32_e32 v18, 19, v3
	s_or_b64 s[28:29], vcc, s[28:29]
	v_cmp_lt_u32_e32 vcc, v18, v9
	v_cmp_ge_u32_e64 s[30:31], v18, v10
	v_add_u32_e32 v19, 24, v3
	s_or_b64 s[30:31], vcc, s[30:31]
	v_cmp_ge_u32_e32 vcc, v19, v9
	v_cmp_lt_u32_e64 s[34:35], v19, v10
	v_mov_b32_e32 v19, 0x1000
	s_and_b64 vcc, vcc, s[34:35]
	v_add_u32_e32 v20, 25, v3
	v_cndmask_b32_e32 v19, 0, v19, vcc
	v_cmp_ge_u32_e32 vcc, v20, v9
	v_cmp_lt_u32_e64 s[34:35], v20, v10
	v_mov_b32_e32 v17, 0x400
	v_mov_b32_e32 v18, 0x800
	v_mov_b32_e32 v20, 0x2000
	s_and_b64 vcc, vcc, s[34:35]
	v_add_u32_e32 v21, 26, v3
	v_cndmask_b32_e64 v12, 32, 0, s[18:19]
	v_cndmask_b32_e64 v17, v17, 0, s[28:29]
	v_cndmask_b32_e64 v18, v18, 0, s[30:31]
	v_cndmask_b32_e32 v20, 0, v20, vcc
	v_cmp_ge_u32_e32 vcc, v21, v9
	v_cmp_lt_u32_e64 s[34:35], v21, v10
	v_add_u32_e32 v22, 27, v3
	v_cndmask_b32_e64 v5, 8, 0, s[14:15]
	v_cndmask_b32_e64 v11, 16, 0, s[16:17]
	v_mov_b32_e32 v14, 0x80
	s_and_b64 vcc, vcc, s[34:35]
	v_cmp_lt_u32_e64 s[34:35], v22, v10
	v_or3_b32 v10, v12, v17, v18
	v_cndmask_b32_e64 v4, 4, 0, s[12:13]
	v_cndmask_b32_e64 v14, v14, 0, s[22:23]
	v_mov_b32_e32 v21, 0x4000
	v_or3_b32 v5, v11, v5, v10
	v_cndmask_b32_e64 v1, 2, 0, s[10:11]
	v_cndmask_b32_e64 v13, 64, 0, s[20:21]
	v_mov_b32_e32 v15, 0x100
	v_mov_b32_e32 v16, 0x200
	v_cndmask_b32_e32 v21, 0, v21, vcc
	v_cmp_ge_u32_e32 vcc, v22, v9
	v_or3_b32 v4, v4, v14, v5
	s_movk_i32 s3, 0x1d1
	v_cndmask_b32_e64 v15, 0, v15, s[24:25]
	v_cndmask_b32_e64 v16, 0, v16, s[26:27]
	v_mov_b32_e32 v9, 0x8000
	s_and_b64 vcc, vcc, s[34:35]
	v_or3_b32 v1, v13, v1, v4
	v_cmp_gt_i32_e64 s[6:7], s3, v72
	s_movk_i32 s3, 0x1000
	s_movk_i32 s4, 0x2000
	v_cndmask_b32_e32 v9, 0, v9, vcc
	v_or3_b32 v1, v15, v16, v1
	v_or_b32_e32 v4, v19, v20
	s_movk_i32 s5, 0x4000
	v_or_b32_e32 v5, v4, v1
	v_or_b32_e32 v9, v21, v9
	v_bitop3_b32 v10, v4, s3, v1 bitop3:0xc8
	v_bitop3_b32 v1, v4, s4, v1 bitop3:0xc8
	s_mov_b32 s40, 0x8000
	v_cmp_eq_u32_e64 s[36:37], 0, v1
	v_bitop3_b32 v1, v9, s5, v5 bitop3:0xc8
	v_cmp_eq_u32_e64 s[38:39], 0, v1
	v_bitop3_b32 v1, v9, s40, v5 bitop3:0xc8
	v_cmp_eq_u32_e64 s[40:41], 0, v1
	v_max_i32_e32 v1, 0xffffffd1, v72
	v_sub_u32_e32 v1, v1, v72
	v_add_u32_e32 v1, 0x1ff, v1
	v_lshlrev_b32_e32 v131, 1, v3
	v_lshrrev_b32_e32 v3, 9, v1
	s_movk_i32 s3, 0x2a00
	v_add_u32_e32 v4, 1, v3
	v_cmp_gt_u32_e64 s[58:59], s3, v1
	s_movk_i32 s3, 0x29ff
	v_and_b32_e32 v132, 0xfffffe00, v1
	v_cmp_lt_u32_e64 s[42:43], s3, v1
	v_and_b32_e32 v1, 0xfffffe, v4
	v_lshlrev_b32_e32 v136, 2, v72
	v_add_u32_e32 v3, -1, v3
	v_lshl_add_u32 v133, v1, 9, v72
	v_cmp_ne_u32_e64 s[48:49], v4, v1
	v_add_u32_e32 v1, 0, v136
	v_lshrrev_b32_e32 v5, 1, v3
	v_cmp_lt_u32_e64 s[44:45], 5, v3
	v_add_u32_e32 v137, 0x9100, v1
	v_lshl_or_b32 v1, v6, 2, v74
	v_lshlrev_b32_e32 v3, 2, v8
	v_bfe_u32 v125, v72, 4, 1
	v_sub_u32_e32 v1, v1, v3
	v_and_b32_e32 v3, 0xc0, v72
	v_ashrrev_i32_e32 v7, 7, v72
	v_sub_u32_e32 v1, v1, v3
	v_mul_u32_u24_e32 v3, 0x7c, v125
	v_sub_u32_e32 v1, v1, v3
	v_lshrrev_b32_e32 v3, 1, v7
	s_movk_i32 s3, 0xf8
	v_mul_lo_u32 v3, v3, s3
	v_add_u32_e32 v5, 1, v5
	v_sub_u32_e32 v1, v1, v3
	v_and_b32_e32 v134, 3, v5
	v_add_u32_e32 v1, 0, v1
	v_and_b32_e32 v124, -2, v7
	v_ashrrev_i32_e32 v81, 31, v80
	v_cmp_eq_u32_e64 s[34:35], 0, v10
	v_add_u32_e32 v73, 0x200, v72
	v_and_b32_e32 v135, -4, v5
	v_cmp_ne_u32_e64 s[46:47], 0, v134
	v_add_u32_e32 v138, 0x92b0, v1
	s_mov_b32 s3, 0x8200
	v_lshlrev_b32_e32 v84, 1, v2
	s_mov_b32 s60, 0x3fb8aa3b
	s_movk_i32 s61, 0xffd0
	s_mov_b32 s82, 0xff800000
	v_lshlrev_b32_e32 v86, 1, v0
	v_mov_b32_e32 v139, 0x4100
	v_mov_b32_e32 v140, 0xff800000
	s_mov_b32 s83, s2
	s_mov_b32 s85, s2
	s_branch .LBB0_2273

.LBB0_2338:
	s_setprio 0
	s_cmp_lt_i32 s67, 30
	s_cbranch_scc1 .LBB0_2392
	s_waitcnt vmcnt(0)
	v_readlane_b32 s4, v232, 0
	v_readlane_b32 s5, v232, 1
	s_waitcnt vmcnt(0) lgkmcnt(0)
	s_barrier
	s_and_saveexec_b64 s[6:7], s[4:5]
	s_cbranch_execz .LBB0_2391
	s_add_i32 s3, 0, 0x20000
	v_mov_b32_e32 v0, s3
	s_waitcnt vmcnt(0) expcnt(0) lgkmcnt(0)
	ds_read_b32 v2, v0
	s_add_i32 s3, 0, 0x20004
	v_mov_b32_e32 v0, s3
	ds_read_b32 v0, v0
	s_waitcnt lgkmcnt(1)
	v_cmp_ne_u32_e32 vcc, 0, v2
	s_cbranch_vccnz .LBB0_2355
	s_add_u32 s8, s68, 0x23718200
	s_addc_u32 s9, s69, 0
	s_add_u32 s10, s68, 0x23718400
	s_addc_u32 s11, s69, 0
	s_add_u32 s12, s68, 0x23718500
	s_addc_u32 s13, s69, 0
	s_add_u32 s14, s68, 0x23718600
	s_addc_u32 s15, s69, 0
	s_add_u32 s16, s68, 0x23718700
	s_addc_u32 s17, s69, 0
	s_add_u32 s18, s68, 0x23718800
	s_addc_u32 s19, s69, 0
	s_add_u32 s20, s68, 0x23718900
	s_addc_u32 s21, s69, 0
	s_add_u32 s22, s68, 0x23718a00
	s_addc_u32 s23, s69, 0
	s_add_u32 s24, s68, 0x23718b00
	s_addc_u32 s25, s69, 0
	s_add_u32 s26, s68, 0x23718c00
	s_addc_u32 s27, s69, 0
	s_add_u32 s28, s68, 0x23718d00
	s_addc_u32 s29, s69, 0
	s_add_u32 s30, s68, 0x23718e00
	s_addc_u32 s31, s69, 0
	s_add_u32 s34, s68, 0x23718f00
	s_addc_u32 s35, s69, 0
	s_add_u32 s36, s68, 0x23719000
	s_load_dword s3, s[0:1], 0x110
	s_addc_u32 s37, s69, 0
	s_add_u32 s38, s68, 0x23719100
	s_addc_u32 s39, s69, 0
	s_add_u32 s40, s68, 0x23719200
	s_addc_u32 s41, s69, 0
	s_waitcnt lgkmcnt(0)
	s_mul_i32 s3, s65, s3
	s_add_u32 s42, s68, 0x23719300
	s_mul_i32 s3, s3, s64
	s_addc_u32 s43, s69, 0
	s_mov_b32 s50, 1
	v_mov_b32_e32 v16, 0
	s_branch .LBB0_2343
